# candidate F + s_setprio 1 for waves 4-7 inside the P5 attention phase
# baseline (speedup 1.0000x reference)
; #define INP(i) ((const float*)ldptr(ptab, (i)))
; __global__ void __launch_bounds__(512, 2) fwd_mega(Args args) {
;     ...
;         } else if (ph == 5) {
;             const float bref5 = attn_logit_bound(INP(8), INP(9), lane, 1.5849625007211562f);
;             attn_build_bias(lds, tid, bref5);
;             __syncthreads();
;             for (int c0 = bx; c0 < 256; c0 += G) { const int c = (G == 256) ? ((c0 & 7) * 32 + (c0 >> 3)) : c0;
;                 const int bh = c >> 3, s = c & 7, bb = bh >> 3, hh = bh & 7;
; #pragma unroll 1
;                 for (int k = 0; k < 2; ++k) { const int qb = k == 0 ? s : 15 - s; const int q0 = qb * 128; const size_t R0 = (size_t)bb * SEQ;
;                     attn_item<0>(lds, PROJ + (R0 + q0) * PROJW + hh * 128, PROJW, PROJ + R0 * PROJW + 1024 + hh * 128, VTA + (size_t)(bb * 8 + hh) * 128 * SEQ, PROJW,
;                                  (q0 + 128) / 64, q0, MIX + (R0 + q0) * DM + hh * 128, DM, nullptr, nullptr, nullptr, nullptr, 0, bref5);
;                     __syncthreads(); } }
.LBB0_111:
	s_mov_b64 s[82:83], s[54:55]
	s_or_b64 exec, exec, s[24:25]
	v_readlane_b32 s14, v253, 8
	v_readlane_b32 s15, v253, 9
	s_andn2_b64 vcc, exec, s[14:15]
	s_waitcnt lgkmcnt(0)
	s_barrier
	s_cbranch_vccnz .LBB0_132
	v_readlane_b32 s14, v255, 51
	s_nop 3
	s_cmp_ge_u32 s14, 4
	s_cbranch_scc0 .Lattn_prio_skip
	s_setprio 1
.Lattn_prio_skip:
	s_add_u32 s0, s28, 0x200
	s_addc_u32 s14, s29, 0
	s_add_u32 s15, s56, 0xb000800
	s_addc_u32 s16, s57, 0
	s_mov_b32 s17, s2
	s_branch .LBB0_114

; #define INP(i) ((const float*)ldptr(ptab, (i)))
; __global__ void __launch_bounds__(512, 2) fwd_mega(Args args) {
;     ...
;             for (int item = bx; item < 512; item += G) gla_stepA(lds, item, PROJ, VTG, GLR, INP(10), INP(11), DST, DECAY);
.LBB0_132:
	s_setprio 0
	v_readlane_b32 s10, v253, 17
	v_readlane_b32 s11, v253, 18
	s_andn2_b64 vcc, exec, s[10:11]
	v_readlane_b32 s10, v255, 8
	v_readlane_b32 s24, v254, 61
	v_readlane_b32 s11, v255, 9
	v_readlane_b32 s25, v254, 62
	v_readlane_b32 s26, v253, 13
	s_mov_b32 s46, s2
	s_movk_i32 s58, 0x5fe
	s_movk_i32 s59, 0x1810
	s_mov_b64 s[54:55], s[82:83]
	s_cbranch_vccz .LBB0_149
